# attention: all waves through deferred-PV path + software-pipelined fast loop (QK then PV(tt-1) with softmax VALU in MFMA gaps), f32 VALU row sums instead of row-sum MFMAs, K tiles DMA'd 3 ahead with K
# speedup vs baseline: 1.3384x; 1.0017x over previous
; #define LAS __attribute__((address_space(3)))
; #define ATT_WAITBAR(N) asm volatile("s_waitcnt vmcnt(" #N ") lgkmcnt(0)\n\ts_barrier" ::: "memory")
; __device__ __forceinline__ void attn_unit(LAS unsigned char* lds, const bf16_t* Qb, const unsigned char* Kimg, const unsigned char* Vimg, bf16_t* AO, int b, int h, int qpos0, int ntiles, int store_limit, ...
;     ...
;     const int qp_w = qpos0 + 32 * qg;
;     const int qpos = qp_w + i32;
;     bf16x8 qf[4];
;     { const int qr = qpos < LSEQ ? qpos : LSEQ - 1; const bf16_t* qp = Qb + (rowbase + qr) * DM + h * 128 + c * 64 + 8 * hi;
; #pragma unroll
;       for (int d0 = 0; d0 < 4; ++d0) qf[d0] = *(const bf16x8*)(qp + 16 * d0); }
;     const int ch_w = qp_w < NMETA ? 0 : 1 + (qp_w - NMETA) / 64;
;     const int T_w = ch_w < ntiles - 1 ? ch_w : ntiles - 1;
;     const unsigned char* kg0 = Kimg + (size_t)(b * 8 + h) * pg8::KV_BH_BYTES + wid * 1024 + lane * 16;
;     const unsigned char* vg0 = Vimg + (size_t)(b * 8 + h) * pg8::KV_BH_BYTES + wid * 1024 + lane * 16;
;     ...
;     const unsigned lds0 = (unsigned)(uintptr_t)lds;
;     ...
;     f32x16 o[4];
; #pragma unroll
;     for (int d = 0; d < 4; ++d)
; #pragma unroll
;         for (int r = 0; r < 16; ++r) o[d][r] = 0.f;
;     bf16x8 pn[4];
; #pragma unroll
;     for (int k = 0; k < 4; ++k) pn[k] = (bf16x8){0, 0, 0, 0, 0, 0, 0, 0};
;     f32x16 osum, negm;
; #pragma unroll
;     for (int r = 0; r < 16; ++r) { osum[r] = 0.f; negm[r] = 0.f; }
;     float m_hat = 0.f;
;     DMA_TILE(0); DMA_TILE(1);
;     ATT_WAITBAR(4);
;     const LAS unsigned char* kfb = lds + A_K + (8 * c + hi) * 1024 + i32 * 16;
;     const LAS unsigned char* vfb = lds + A_V + ((lane >> 4) & 1) * 32 + (lane & 3) * 8 + (4 * hi + ((lane & 15) >> 2)) * 64;
;     ...
;     if (c == 0) {
;         for (int tt = 0; tt < ntiles; ++tt) {
;             ATT_COMMON(tt)
;             if (tt <= T_w) att_qs(pn, o, osum, negm, qf, m_hat, kb_, scr, lut, hi, i32, near_, lb_, tt == 0);
;             DMA_TILE(tt + 2);
;             if (tt <= T_w) att_pv(pn, o, osum, vfb + (tt & 3) * 16384);
;             ATT_WAITBAR(4);
;         }
;     } else {
;         for (int tt = 0; tt < ntiles; ++tt) {
;             ATT_COMMON(tt)
;             if (tt >= 1 && tt - 1 <= T_w) att_pv(pn, o, osum, vfb + ((tt - 1) & 3) * 16384);
;             if (tt <= T_w) att_qs(pn, o, osum, negm, qf, m_hat, kb_, scr, lut, hi, i32, near_, lb_, tt == 0);
.LBB0_676:
	s_or_b64 exec, exec, s[0:1]
	s_bfe_u32 s48, s9, 0x20006
	s_lshl_b32 s46, s48, 5
	s_add_i32 s46, s46, s11
	s_lshr_b32 s45, s10, 3
	v_add_u32_e32 v4, s46, v168
	s_mulk_i32 s45, 0x4010
	v_min_u32_e32 v0, 0x400f, v4
	v_add_lshl_u32 v0, v0, s45, 11
	s_lshr_b32 s47, s9, 8
	v_lshl_add_u64 v[2:3], s[18:19], 0, v[0:1]
	s_lshl_b32 s16, s49, 8
	v_lshl_add_u64 v[2:3], v[2:3], 0, s[16:17]
	s_lshl_b32 s16, s47, 7
	v_lshl_add_u64 v[2:3], v[2:3], 0, s[16:17]
	v_mov_b32_e32 v177, v1
	v_lshl_add_u64 v[2:3], v[2:3], 0, v[176:177]
	global_load_dwordx4 v[146:149], v[2:3], off
	global_load_dwordx4 v[150:153], v[2:3], off offset:32
	global_load_dwordx4 v[154:157], v[2:3], off offset:64
	global_load_dwordx4 v[158:161], v[2:3], off offset:96
	s_lshr_b32 s11, s9, 6
	s_lshl_b32 s0, s11, 7
	s_add_i32 s51, s0, 0
	v_sub_co_u32_e64 v0, s[0:1], s46, 16
	s_nop 0
	v_readfirstlane_b32 s16, v0
	s_lshr_b32 s16, s16, 6
	s_lshl_b32 s53, s11, 10
	s_add_i32 s51, s51, 0x20400
	s_add_i32 s16, s16, 1
	s_add_i32 s52, s50, -1
	s_mul_i32 s28, s10, 0x408000
	s_ashr_i32 s54, s53, 31
	s_add_u32 s10, s42, s28
	s_addc_u32 s11, s43, 0
	s_add_u32 s10, s10, s53
	s_addc_u32 s11, s11, s54
	s_and_b64 s[0:1], s[0:1], exec
	s_cselect_b32 s29, 0, s16
	s_add_u32 s0, s12, s28
	s_addc_u32 s1, s13, 0
	s_add_u32 s0, s0, s53
	s_addc_u32 s1, s1, s54
	v_lshl_add_u64 v[178:179], s[0:1], 0, v[166:167]
	s_add_i32 s28, s53, 0
	s_mov_b32 s1, m0
	s_mov_b32 m0, s28
	s_nop 0
	global_load_lds_dwordx4 v[178:179], off
	s_mov_b32 m0, s1
	v_lshl_add_u64 v[180:181], s[10:11], 0, v[166:167]
	s_add_i32 s0, s28, 0x10000
	v_lshl_add_u64 v[2:3], v[178:179], 0, s[22:23]
	s_add_i32 s1, s28, 0x2000
	s_mov_b32 s10, m0
	s_mov_b32 m0, s1
	s_nop 0
	global_load_lds_dwordx4 v[2:3], off
	s_mov_b32 m0, s10
	s_min_u32 s54, s29, s52
	s_mov_b32 s1, m0
	s_mov_b32 m0, s0
	s_nop 0
	global_load_lds_dwordx4 v[180:181], off
	s_mov_b32 m0, s1
	s_add_i32 s0, s28, 0x12000
	s_cmp_eq_u32 s52, 0
	v_lshl_add_u64 v[2:3], v[180:181], 0, s[22:23]
	s_mov_b32 s1, m0
	s_mov_b32 m0, s0
	s_nop 0
	global_load_lds_dwordx4 v[2:3], off
	s_mov_b32 m0, s1
	s_cselect_b32 s16, 0, 0x4000
	s_add_i32 s0, s28, 0x4000
	v_lshl_add_u64 v[2:3], v[178:179], 0, s[16:17]
	s_mov_b32 s10, m0
	s_mov_b32 m0, s0
	s_nop 0
	global_load_lds_dwordx4 v[2:3], off
	s_mov_b32 m0, s10
	v_lshl_add_u64 v[2:3], v[2:3], 0, s[22:23]
	s_add_i32 s0, s28, 0x6000
	s_mov_b32 s10, m0
	s_mov_b32 m0, s0
	s_nop 0
	global_load_lds_dwordx4 v[2:3], off
	s_mov_b32 m0, s10
	s_add_i32 s1, s28, 0x14000
	v_lshl_add_u64 v[2:3], v[180:181], 0, s[16:17]
	s_mov_b32 s0, m0
	s_mov_b32 m0, s1
	s_nop 0
	global_load_lds_dwordx4 v[2:3], off
	s_mov_b32 m0, s0
	v_lshl_add_u64 v[2:3], v[2:3], 0, s[22:23]
	s_add_i32 s0, s28, 0x16000
	s_mov_b32 s1, m0
	s_mov_b32 m0, s0
	s_nop 0
	global_load_lds_dwordx4 v[2:3], off
	s_mov_b32 m0, s1
	s_waitcnt vmcnt(4) lgkmcnt(0)
	s_barrier
	s_cmpk_lt_u32 s9, 0x100
	s_cselect_b64 s[0:1], -1, 0
	v_sub_u32_e32 v225, v186, v4
	v_lshl_add_u32 v177, s47, 13, v184
	v_add_u32_e32 v226, 0x80, v225
	v_lshl_add_u32 v224, v168, 2, s51
	s_mov_b64 s[10:11], -1
	s_and_b64 vcc, exec, s[0:1]
	s_cmpk_gt_u32 s46, 0x99
	s_setprio 1
	ds_read_b128 v[2:5], v177
	ds_read_b128 v[6:9], v177 offset:2048
	s_waitcnt vmcnt(3) lgkmcnt(1)
	v_mfma_f32_32x32x16_bf16 v[32:47], v[2:5], v[146:149], 0
	ds_read_b128 v[10:13], v177 offset:4096
	s_waitcnt vmcnt(2) lgkmcnt(1)
	v_mfma_f32_32x32x16_bf16 v[32:47], v[6:9], v[150:153], v[32:47]
	ds_read_b128 v[2:5], v177 offset:6144
	s_waitcnt vmcnt(1) lgkmcnt(1)
	v_mfma_f32_32x32x16_bf16 v[32:47], v[10:13], v[154:157], v[32:47]
	s_waitcnt vmcnt(0) lgkmcnt(0)
	v_mfma_f32_32x32x16_bf16 v[32:47], v[2:5], v[158:161], v[32:47]
	s_cbranch_scc1 .LBB0_679
	v_max_i32_e32 v2, 0xffffff7f, v225
	v_lshl_add_u32 v9, v2, 2, s37
	v_max_i32_e32 v2, 0xffffff7e, v225
	v_max_i32_e32 v3, 0xffffff7d, v225
	v_max_i32_e32 v4, 0xffffff78, v225
	v_max_i32_e32 v5, 0xffffff77, v225
	v_max_i32_e32 v6, 0xffffff76, v225
	v_max_i32_e32 v7, 0xffffff75, v225
	v_max_i32_e32 v0, 0, v226
	v_lshl_add_u32 v2, v2, 2, s37
	v_lshl_add_u32 v3, v3, 2, s37
	v_lshl_add_u32 v4, v4, 2, s37
	v_lshl_add_u32 v5, v5, 2, s37
	v_lshl_add_u32 v6, v6, 2, s37
	v_lshl_add_u32 v7, v7, 2, s37
	v_lshl_add_u32 v0, v0, 2, s37
	ds_read_b32 v2, v2 offset:520
	ds_read_b32 v3, v3 offset:524
	ds_read_b32 v4, v4 offset:544
	ds_read_b32 v6, v6 offset:552
	ds_read_b32 v7, v7 offset:556
	ds_read_b32 v5, v5 offset:548
	ds_read_b32 v8, v0
	ds_read_b32 v9, v9 offset:516
	s_waitcnt lgkmcnt(6)
	v_pk_add_f32 v[34:35], v[34:35], v[2:3]
	s_waitcnt lgkmcnt(3)
	v_pk_add_f32 v[38:39], v[38:39], v[6:7]
	s_waitcnt lgkmcnt(2)
	v_pk_add_f32 v[36:37], v[36:37], v[4:5]
	s_waitcnt lgkmcnt(0)
	v_pk_add_f32 v[32:33], v[32:33], v[8:9]

; __device__ __forceinline__ unsigned pk2(float lo, float hi) { f32x2_t v = {lo, hi}; bf16x2_t b = __builtin_convertvector(v, bf16x2_t); return __builtin_bit_cast(unsigned, b); }
; __device__ __forceinline__ void att_qs(bf16x8 (&pn)[4], f32x16 (&o)[4], f32x16& osum, f32x16& negm, const bf16x8 (&qf)[4], float& m_hat, ...
;     ...
;     kf[0] = ATT_KREAD(0); kf[1] = ATT_KREAD(1); kf[2] = ATT_KREAD(2); kf[3] = ATT_KREAD(3);
;     __builtin_amdgcn_sched_barrier(0);
; #pragma unroll
;     for (int i = 0; i < 8; ++i) {
;         if (i == 0) c0 = __builtin_amdgcn_mfma_f32_32x32x16_bf16(kf[0], qf[0], negm, 0, 0, 0);
;         else if (i == 1) c1 = __builtin_amdgcn_mfma_f32_32x32x16_bf16(kf[1], qf[0], negm, 0, 0, 0);
;         else if ((i & 1) == 0) c0 = __builtin_amdgcn_mfma_f32_32x32x16_bf16(kf[i & 3], qf[i >> 1], c0, 0, 0, 0);
;         else c1 = __builtin_amdgcn_mfma_f32_32x32x16_bf16(kf[i & 3], qf[i >> 1], c1, 0, 0, 0);
;         if (i + 4 < 8) kf[i & 3] = ATT_KREAD(i + 4);
;         __builtin_amdgcn_sched_barrier(0);
;     }
;     ...
;     unsigned paw[16];
; #pragma unroll
;     for (int g = 0; g < 8; ++g) { const int b = (4 * g) & 15;
;         const float v0 = __builtin_amdgcn_exp2f(g < 4 ? c0[b] : c1[b]), v1 = __builtin_amdgcn_exp2f(g < 4 ? c0[b + 1] : c1[b + 1]);
;         const float v2 = __builtin_amdgcn_exp2f(g < 4 ? c0[b + 2] : c1[b + 2]), v3 = __builtin_amdgcn_exp2f(g < 4 ? c0[b + 3] : c1[b + 3]);
;         paw[2 * g] = pk2(v0, v1); paw[2 * g + 1] = pk2(v2, v3); }
; #pragma unroll
;     for (int k = 0; k < 4; ++k) { u32x4 w; w.x = paw[4 * k]; w.y = paw[4 * k + 1]; w.z = paw[4 * k + 2]; w.w = paw[4 * k + 3]; pn[k] = __builtin_bit_cast(bf16x8, w); }
.Latt_fast_entry:
	v_mov_b32_e32 v242, s8
	v_mov_b32_e32 v243, s8
	v_mov_b32_e32 v244, s8
	v_mov_b32_e32 v245, s8
	v_mov_b32_e32 v248, v17
	v_mov_b32_e32 v118, v16
	s_mov_b32 s101, 0
	v_mfma_f32_32x32x16_bf16 v[18:33], v[134:137], v[242:245], v[18:33]
	v_mfma_f32_32x32x16_bf16 v[18:33], v[114:117], v[242:245], v[18:33]
	v_mfma_f32_32x32x16_bf16 v[18:33], v[124:127], v[242:245], v[18:33]
	v_mfma_f32_32x32x16_bf16 v[18:33], v[120:123], v[242:245], v[18:33]
	v_mov_b32_e32 v243, 0
	v_mov_b32_e32 v244, 0
	s_add_i32 s10, s57, 0xffff4000
	s_and_b32 s10, s10, 0xc000
	v_add_u32_e32 v133, s10, v185
	s_add_i32 s9, s57, 0xffff8000
	s_and_b32 s9, s9, 0xc000
	v_add_u32_e32 v132, s9, v177
	ds_read_b128 v[128:131], v132
	ds_read_b128 v[138:141], v132 offset:2048
	ds_read_b128 v[142:145], v132 offset:4096
	ds_read_b128 v[250:253], v132 offset:6144
	s_add_i32 s9, s56, 2
	s_min_u32 s9, s9, s52
	s_lshl_b32 s10, s9, 14
	s_mov_b32 s11, 0
	s_and_b32 s9, s57, 0xc000
	s_add_i32 s9, s9, s53
	s_mov_b32 m0, s9
	v_lshl_add_u64 v[254:255], v[178:179], 0, s[10:11]
	global_load_lds_dwordx4 v[254:255], off
	s_add_i32 m0, s9, 0x2000
	v_lshl_add_u64 v[254:255], v[254:255], 0, s[22:23]
	global_load_lds_dwordx4 v[254:255], off
	s_add_i32 s9, s56, 2
	s_min_u32 s9, s9, s52
	s_lshl_b32 s100, s9, 14
	s_and_b32 s99, s57, 0xc000
	s_add_i32 s99, s99, s53
	s_add_i32 s9, s56, 3
	s_min_u32 s9, s9, s52
	s_lshl_b32 s10, s9, 14
	s_mov_b32 s11, 0
	s_add_i32 s9, s57, 0x4000
	s_and_b32 s9, s9, 0xc000
	s_add_i32 s9, s9, s53
	s_waitcnt lgkmcnt(3)
	v_mfma_f32_32x32x16_bf16 v[226:241], v[128:131], v[146:149], v[98:113]
	ds_read_b128 v[128:131], v132 offset:512
	s_mov_b32 m0, s9
	v_lshl_add_u64 v[254:255], v[178:179], 0, s[10:11]
	global_load_lds_dwordx4 v[254:255], off
	s_waitcnt lgkmcnt(3)
	v_mfma_f32_32x32x16_bf16 v[226:241], v[138:141], v[150:153], v[226:241]
	ds_read_b128 v[138:141], v132 offset:2560
	s_add_i32 m0, s9, 0x2000
	v_lshl_add_u64 v[254:255], v[254:255], 0, s[22:23]
	global_load_lds_dwordx4 v[254:255], off
	s_waitcnt lgkmcnt(3)
	v_mfma_f32_32x32x16_bf16 v[226:241], v[142:145], v[154:157], v[226:241]
	ds_read_b128 v[142:145], v132 offset:4608
	s_add_i32 m0, s99, 0x10000
	v_lshl_add_u64 v[254:255], v[180:181], 0, s[100:101]
	global_load_lds_dwordx4 v[254:255], off
	s_waitcnt lgkmcnt(3)
	v_mfma_f32_32x32x16_bf16 v[226:241], v[250:253], v[158:161], v[226:241]
	ds_read_b128 v[250:253], v132 offset:6656
	s_add_i32 m0, s99, 0x12000
	v_lshl_add_u64 v[254:255], v[254:255], 0, s[22:23]
	global_load_lds_dwordx4 v[254:255], off
	s_waitcnt lgkmcnt(3)
	v_mfma_f32_32x32x16_bf16 v[2:17], v[128:131], v[146:149], v[98:113]
	ds_read_b64_tr_b16 v[128:129], v133
	ds_read_b64_tr_b16 v[130:131], v133 offset:512
	s_waitcnt lgkmcnt(4)
	v_mfma_f32_32x32x16_bf16 v[2:17], v[138:141], v[150:153], v[2:17]
	ds_read_b64_tr_b16 v[138:139], v133 offset:4096
	ds_read_b64_tr_b16 v[140:141], v133 offset:4608
	s_waitcnt lgkmcnt(5)
	v_mfma_f32_32x32x16_bf16 v[2:17], v[142:145], v[154:157], v[2:17]
	ds_read_b64_tr_b16 v[142:143], v133 offset:8192
	ds_read_b64_tr_b16 v[144:145], v133 offset:8704
	s_waitcnt lgkmcnt(6)
	v_mfma_f32_32x32x16_bf16 v[2:17], v[250:253], v[158:161], v[2:17]
	ds_read_b64_tr_b16 v[250:251], v133 offset:12288
	ds_read_b64_tr_b16 v[252:253], v133 offset:12800
	s_branch .Latt_fast_pv
.Latt_fast_top:
	s_add_i32 s10, s57, 0xffff4000
	s_and_b32 s10, s10, 0xc000
	v_add_u32_e32 v133, s10, v185
	s_add_i32 s9, s56, 2
	s_min_u32 s9, s9, s52
	s_lshl_b32 s100, s9, 14
	s_and_b32 s99, s57, 0xc000
	s_add_i32 s99, s99, s53
	s_add_i32 s9, s56, 3
	s_min_u32 s9, s9, s52
	s_lshl_b32 s10, s9, 14
	s_mov_b32 s11, 0
	s_add_i32 s9, s57, 0x4000
	s_and_b32 s9, s9, 0xc000
	s_add_i32 s9, s9, s53
	v_exp_f32_e32 v2, v2
	v_exp_f32_e32 v3, v3
	v_add_f32_e32 v243, v243, v2
	v_exp_f32_e32 v4, v4
	v_add_f32_e32 v244, v244, v3
	v_exp_f32_e32 v5, v5
	v_add_f32_e32 v243, v243, v4
	v_cvt_pk_bf16_f32 v124, v2, v3
	v_add_f32_e32 v244, v244, v5
	v_exp_f32_e32 v6, v6
	v_exp_f32_e32 v7, v7
	v_add_f32_e32 v243, v243, v6
	s_waitcnt lgkmcnt(3)
	v_mfma_f32_32x32x16_bf16 v[226:241], v[128:131], v[146:149], v[98:113]
	ds_read_b128 v[128:131], v132 offset:512
	s_mov_b32 m0, s9
	v_lshl_add_u64 v[254:255], v[178:179], 0, s[10:11]
	global_load_lds_dwordx4 v[254:255], off
	v_cvt_pk_bf16_f32 v125, v4, v5
	v_add_f32_e32 v244, v244, v7
	v_exp_f32_e32 v8, v8
	v_exp_f32_e32 v9, v9
	v_add_f32_e32 v243, v243, v8
	v_cvt_pk_bf16_f32 v126, v6, v7
	v_add_f32_e32 v244, v244, v9
	s_waitcnt lgkmcnt(3)
	v_mfma_f32_32x32x16_bf16 v[226:241], v[138:141], v[150:153], v[226:241]
	ds_read_b128 v[138:141], v132 offset:2560
	s_add_i32 m0, s9, 0x2000
	v_lshl_add_u64 v[254:255], v[254:255], 0, s[22:23]
	global_load_lds_dwordx4 v[254:255], off
	v_cvt_pk_bf16_f32 v127, v8, v9
	v_exp_f32_e32 v10, v10
	v_exp_f32_e32 v11, v11
	v_add_f32_e32 v243, v243, v10
	v_exp_f32_e32 v12, v12
	v_add_f32_e32 v244, v244, v11
	v_exp_f32_e32 v13, v13
	s_waitcnt lgkmcnt(3)
	v_mfma_f32_32x32x16_bf16 v[226:241], v[142:145], v[154:157], v[226:241]
	ds_read_b128 v[142:145], v132 offset:4608
	s_add_i32 m0, s99, 0x10000
	v_lshl_add_u64 v[254:255], v[180:181], 0, s[100:101]
	global_load_lds_dwordx4 v[254:255], off
	v_add_f32_e32 v243, v243, v12
	v_cvt_pk_bf16_f32 v120, v10, v11
	v_add_f32_e32 v244, v244, v13
	v_exp_f32_e32 v14, v14
	v_exp_f32_e32 v15, v15
	v_add_f32_e32 v243, v243, v14
	v_cvt_pk_bf16_f32 v121, v12, v13
	s_waitcnt lgkmcnt(3)
	v_mfma_f32_32x32x16_bf16 v[226:241], v[250:253], v[158:161], v[226:241]
	ds_read_b128 v[250:253], v132 offset:6656
	s_add_i32 m0, s99, 0x12000
	v_lshl_add_u64 v[254:255], v[254:255], 0, s[22:23]
	global_load_lds_dwordx4 v[254:255], off
	v_add_f32_e32 v244, v244, v15
	v_exp_f32_e32 v16, v16
	v_exp_f32_e32 v17, v17
	v_add_f32_e32 v243, v243, v16
	v_cvt_pk_bf16_f32 v122, v14, v15
	v_add_f32_e32 v244, v244, v17
	v_cvt_pk_bf16_f32 v123, v16, v17
	s_waitcnt lgkmcnt(3)
	v_mfma_f32_32x32x16_bf16 v[2:17], v[128:131], v[146:149], v[98:113]
	ds_read_b64_tr_b16 v[128:129], v133
	ds_read_b64_tr_b16 v[130:131], v133 offset:512
	s_waitcnt lgkmcnt(4)
	v_mfma_f32_32x32x16_bf16 v[2:17], v[138:141], v[150:153], v[2:17]
	ds_read_b64_tr_b16 v[138:139], v133 offset:4096
	ds_read_b64_tr_b16 v[140:141], v133 offset:4608
	s_waitcnt lgkmcnt(5)
	v_mfma_f32_32x32x16_bf16 v[2:17], v[142:145], v[154:157], v[2:17]
	ds_read_b64_tr_b16 v[142:143], v133 offset:8192
	ds_read_b64_tr_b16 v[144:145], v133 offset:8704
	s_waitcnt lgkmcnt(6)
	v_mfma_f32_32x32x16_bf16 v[2:17], v[250:253], v[158:161], v[2:17]
	ds_read_b64_tr_b16 v[250:251], v133 offset:12288
	ds_read_b64_tr_b16 v[252:253], v133 offset:12800
; __device__ __forceinline__ int crow(int r, int hi) { return (r & 3) + 8 * (r >> 2) + 4 * hi; }
; __device__ __forceinline__ void att_qs(bf16x8 (&pn)[4], f32x16 (&o)[4], f32x16& osum, f32x16& negm, const bf16x8 (&qf)[4], float& m_hat, ...
;     ...
;     rm = xhalf_max(rm);
;     if (first_tile) {
;         m_hat += rm;
; #pragma unroll
;         for (int r = 0; r < 16; ++r) { c0[r] -= rm; c1[r] -= rm; negm[r] = -m_hat; }
;     } else if (__any(rm > 8.0f)) {
;         const float dl = fmaxf(rm, 0.f); m_hat += dl; const float f = __builtin_amdgcn_exp2f(-dl);
; #pragma unroll
;         for (int r = 0; r < 16; ++r) { c0[r] -= dl; c1[r] -= dl; negm[r] = -m_hat; }
;         if (hi == 0) scr[i32] = f;
;         asm volatile("s_waitcnt lgkmcnt(0)" ::: "memory");
; #pragma unroll
;         for (int r = 0; r < 16; ++r) { const float fr_ = scr[crow(r, hi)]; osum[r] *= fr_;
; #pragma unroll
;             for (int d = 0; d < 4; ++d) o[d][r] *= fr_; }
;     }
;     unsigned paw[16];
; #pragma unroll
;     for (int g = 0; g < 8; ++g) { const int b = (4 * g) & 15;
;         const float v0 = __builtin_amdgcn_exp2f(g < 4 ? c0[b] : c1[b]), v1 = __builtin_amdgcn_exp2f(g < 4 ? c0[b + 1] : c1[b + 1]);
;         const float v2 = __builtin_amdgcn_exp2f(g < 4 ? c0[b + 2] : c1[b + 2]), v3 = __builtin_amdgcn_exp2f(g < 4 ? c0[b + 3] : c1[b + 3]);
;         paw[2 * g] = pk2(v0, v1); paw[2 * g + 1] = pk2(v2, v3); }
; #pragma unroll
;     for (int k = 0; k < 4; ++k) { u32x4 w; w.x = paw[4 * k]; w.y = paw[4 * k + 1]; w.z = paw[4 * k + 2]; w.w = paw[4 * k + 3]; pn[k] = __builtin_bit_cast(bf16x8, w); }
; __device__ __forceinline__ void att_pv(const bf16x8 (&pp)[4], f32x16 (&o)[4], f32x16& osum, const LAS unsigned char* vb) {
;     ...
;     const bf16x8 ones = (bf16x8){0x3F80, 0x3F80, 0x3F80, 0x3F80, 0x3F80, 0x3F80, 0x3F80, 0x3F80};
;     ATT_VREADK(0);
; #pragma unroll
;     for (int ks = 0; ks < 4; ++ks) {
;         if (ks + 1 < 4) ATT_VREADK(ks + 1);
;         osum = __builtin_amdgcn_mfma_f32_32x32x16_bf16(pp[ks], ones, osum, 0, 0, 0);
; #pragma unroll
;         for (int d = 0; d < 4; ++d) { const int bk = ks & 1;
;             const bf16x8 vf = (bf16x8){vl[bk][d][0], vl[bk][d][1], vl[bk][d][2], vl[bk][d][3], vh[bk][d][0], vh[bk][d][1], vh[bk][d][2], vh[bk][d][3]};
;             o[d] = __builtin_amdgcn_mfma_f32_32x32x16_bf16(pp[ks], vf, o[d], 0, 0, 0); }
;     }
.Latt_fast_pv:
	s_waitcnt lgkmcnt(6)
	v_mfma_f32_32x32x16_bf16 v[34:49], v[134:137], v[128:131], v[34:49]
	ds_read_b64_tr_b16 v[128:129], v133 offset:1024
	ds_read_b64_tr_b16 v[130:131], v133 offset:1536
	s_waitcnt lgkmcnt(6)
	v_mfma_f32_32x32x16_bf16 v[50:65], v[134:137], v[138:141], v[50:65]
	ds_read_b64_tr_b16 v[138:139], v133 offset:5120
	ds_read_b64_tr_b16 v[140:141], v133 offset:5632
	s_waitcnt lgkmcnt(6)
	v_mfma_f32_32x32x16_bf16 v[66:81], v[134:137], v[142:145], v[66:81]
	ds_read_b64_tr_b16 v[142:143], v133 offset:9216
	ds_read_b64_tr_b16 v[144:145], v133 offset:9728
	s_waitcnt lgkmcnt(6)
	v_mfma_f32_32x32x16_bf16 v[82:97], v[134:137], v[250:253], v[82:97]
	ds_read_b64_tr_b16 v[250:251], v133 offset:13312
	ds_read_b64_tr_b16 v[252:253], v133 offset:13824
	s_waitcnt lgkmcnt(6)
	v_mfma_f32_32x32x16_bf16 v[34:49], v[114:117], v[128:131], v[34:49]
	ds_read_b64_tr_b16 v[128:129], v133 offset:2048
	ds_read_b64_tr_b16 v[130:131], v133 offset:2560
	v_max3_f32 v0, v226, v227, v228
	v_max3_f32 v225, v2, v3, v4
	v_max3_f32 v0, v0, v229, v230
	v_max3_f32 v225, v225, v5, v6
	v_max3_f32 v0, v0, v231, v232
	s_waitcnt lgkmcnt(6)
	v_mfma_f32_32x32x16_bf16 v[50:65], v[114:117], v[138:141], v[50:65]
	ds_read_b64_tr_b16 v[138:139], v133 offset:6144
	ds_read_b64_tr_b16 v[140:141], v133 offset:6656
	v_max3_f32 v225, v225, v7, v8
	v_max3_f32 v0, v0, v233, v234
	v_max3_f32 v225, v225, v9, v10
	v_max3_f32 v0, v0, v235, v236
	s_waitcnt lgkmcnt(6)
	v_mfma_f32_32x32x16_bf16 v[66:81], v[114:117], v[142:145], v[66:81]
	ds_read_b64_tr_b16 v[142:143], v133 offset:10240
	ds_read_b64_tr_b16 v[144:145], v133 offset:10752
	v_max3_f32 v225, v225, v11, v12
	v_max3_f32 v0, v0, v237, v238
	v_max3_f32 v225, v225, v13, v14
	v_max3_f32 v0, v0, v239, v240
	s_waitcnt lgkmcnt(6)
	v_mfma_f32_32x32x16_bf16 v[82:97], v[114:117], v[250:253], v[82:97]
	ds_read_b64_tr_b16 v[250:251], v133 offset:14336
	ds_read_b64_tr_b16 v[252:253], v133 offset:14848
	v_max3_f32 v225, v225, v15, v16
	v_max3_f32 v0, v0, v225, v241
	v_max3_f32 v0, v0, v17, v17
	v_mov_b32_e32 v225, v0
	s_nop 1
	v_permlane32_swap_b32_e32 v0, v225
	v_max_f32_e32 v0, v0, v225
	v_cmp_lt_f32_e32 vcc, s36, v0
	s_cbranch_vccnz .Latt_fast_rescale
	s_waitcnt lgkmcnt(6)
	v_mfma_f32_32x32x16_bf16 v[34:49], v[124:127], v[128:131], v[34:49]
	ds_read_b64_tr_b16 v[128:129], v133 offset:3072
	ds_read_b64_tr_b16 v[130:131], v133 offset:3584
	v_exp_f32_e32 v226, v226
	v_exp_f32_e32 v227, v227
	v_add_f32_e32 v243, v243, v226
	v_exp_f32_e32 v228, v228
	v_add_f32_e32 v244, v244, v227
	s_waitcnt lgkmcnt(6)
	v_mfma_f32_32x32x16_bf16 v[50:65], v[124:127], v[138:141], v[50:65]
	ds_read_b64_tr_b16 v[138:139], v133 offset:7168
	ds_read_b64_tr_b16 v[140:141], v133 offset:7680
	v_exp_f32_e32 v229, v229
	v_add_f32_e32 v243, v243, v228
	v_cvt_pk_bf16_f32 v134, v226, v227
	v_add_f32_e32 v244, v244, v229
	v_exp_f32_e32 v230, v230
	s_waitcnt lgkmcnt(6)
	v_mfma_f32_32x32x16_bf16 v[66:81], v[124:127], v[142:145], v[66:81]
	ds_read_b64_tr_b16 v[142:143], v133 offset:11264
	ds_read_b64_tr_b16 v[144:145], v133 offset:11776
	v_exp_f32_e32 v231, v231
	v_add_f32_e32 v243, v243, v230
	v_cvt_pk_bf16_f32 v135, v228, v229
	v_add_f32_e32 v244, v244, v231
	v_exp_f32_e32 v232, v232
	s_waitcnt lgkmcnt(6)
	v_mfma_f32_32x32x16_bf16 v[82:97], v[124:127], v[250:253], v[82:97]
	ds_read_b64_tr_b16 v[250:251], v133 offset:15360
	ds_read_b64_tr_b16 v[252:253], v133 offset:15872
	v_exp_f32_e32 v233, v233
	v_add_f32_e32 v243, v243, v232
	v_cvt_pk_bf16_f32 v136, v230, v231
	v_add_f32_e32 v244, v244, v233
	v_cvt_pk_bf16_f32 v137, v232, v233
	s_waitcnt lgkmcnt(6)
	v_mfma_f32_32x32x16_bf16 v[34:49], v[120:123], v[128:131], v[34:49]
	s_add_i32 s58, s57, 0xffffc000
	s_and_b32 s58, s58, 0xc000
	v_add_u32_e32 v132, s58, v177
	ds_read_b128 v[128:131], v132
	v_exp_f32_e32 v234, v234
	v_exp_f32_e32 v235, v235
	v_add_f32_e32 v243, v243, v234
	v_exp_f32_e32 v236, v236
	v_add_f32_e32 v244, v244, v235
	s_waitcnt lgkmcnt(5)
	v_mfma_f32_32x32x16_bf16 v[50:65], v[120:123], v[138:141], v[50:65]
	ds_read_b128 v[138:141], v132 offset:2048
	v_exp_f32_e32 v237, v237
	v_add_f32_e32 v243, v243, v236
	v_cvt_pk_bf16_f32 v114, v234, v235
	v_add_f32_e32 v244, v244, v237
	v_exp_f32_e32 v238, v238
	s_waitcnt lgkmcnt(4)
	v_mfma_f32_32x32x16_bf16 v[66:81], v[120:123], v[142:145], v[66:81]
	ds_read_b128 v[142:145], v132 offset:4096
	v_exp_f32_e32 v239, v239
	v_add_f32_e32 v243, v243, v238
	v_cvt_pk_bf16_f32 v115, v236, v237
	v_add_f32_e32 v244, v244, v239
	v_exp_f32_e32 v240, v240
	s_waitcnt lgkmcnt(3)
	v_mfma_f32_32x32x16_bf16 v[82:97], v[120:123], v[250:253], v[82:97]
	ds_read_b128 v[250:253], v132 offset:6144
	v_exp_f32_e32 v241, v241
	v_add_f32_e32 v243, v243, v240
	v_cvt_pk_bf16_f32 v116, v238, v239
	v_add_f32_e32 v244, v244, v241
	v_cvt_pk_bf16_f32 v117, v240, v241
.Latt_fast_end:
	s_add_i32 s56, s56, 1
	s_addk_i32 s57, 0x4000
	s_add_i32 s55, s55, 64
	s_cmp_eq_u32 s50, s56
	s_cbranch_scc1 .Latt_fast_exit
	s_cmp_le_u32 s56, s54
	s_cbranch_scc0 .Latt_fast_exit
	s_cmpk_lt_i32 s55, 0xffa6
	s_cbranch_scc0 .Latt_fast_exit
	s_waitcnt vmcnt(4)
	s_barrier
	s_branch .Latt_fast_top
; #define LAS __attribute__((address_space(3)))
; __device__ __forceinline__ unsigned pk2(float lo, float hi) { f32x2_t v = {lo, hi}; bf16x2_t b = __builtin_convertvector(v, bf16x2_t); return __builtin_bit_cast(unsigned, b); }
; __device__ __forceinline__ int crow(int r, int hi) { return (r & 3) + 8 * (r >> 2) + 4 * hi; }
; #define ATT_VREADK(ks) do { _Pragma("unroll") for (int d_ = 0; d_ < 4; ++d_) { vl[(ks) & 1][d_] = vtr(vb + d_ * 4096 + (ks) * 1024); vh[(ks) & 1][d_] = vtr(vb + d_ * 4096 + (ks) * 1024 + 512); } } while (0)
; __device__ __forceinline__ void att_qs(bf16x8 (&pn)[4], f32x16 (&o)[4], f32x16& osum, f32x16& negm, const bf16x8 (&qf)[4], float& m_hat, ...
;     ...
;         if (hi == 0) scr[i32] = f;
;         asm volatile("s_waitcnt lgkmcnt(0)" ::: "memory");
; #pragma unroll
;         for (int r = 0; r < 16; ++r) { const float fr_ = scr[crow(r, hi)]; osum[r] *= fr_;
;     ...
;     unsigned paw[16];
; #pragma unroll
;     for (int g = 0; g < 8; ++g) { const int b = (4 * g) & 15;
;         const float v0 = __builtin_amdgcn_exp2f(g < 4 ? c0[b] : c1[b]), v1 = __builtin_amdgcn_exp2f(g < 4 ? c0[b + 1] : c1[b + 1]);
;         const float v2 = __builtin_amdgcn_exp2f(g < 4 ? c0[b + 2] : c1[b + 2]), v3 = __builtin_amdgcn_exp2f(g < 4 ? c0[b + 3] : c1[b + 3]);
;         paw[2 * g] = pk2(v0, v1); paw[2 * g + 1] = pk2(v2, v3); }
; #pragma unroll
;     for (int k = 0; k < 4; ++k) { u32x4 w; w.x = paw[4 * k]; w.y = paw[4 * k + 1]; w.z = paw[4 * k + 2]; w.w = paw[4 * k + 3]; pn[k] = __builtin_bit_cast(bf16x8, w); }
;     __builtin_amdgcn_s_setprio(0);
; }
; __device__ __forceinline__ void att_pv(const bf16x8 (&pp)[4], f32x16 (&o)[4], f32x16& osum, const LAS unsigned char* vb) {
;     s16x4 vl[2][4], vh[2][4];
;     ...
;     const bf16x8 ones = (bf16x8){0x3F80, 0x3F80, 0x3F80, 0x3F80, 0x3F80, 0x3F80, 0x3F80, 0x3F80};
;     ATT_VREADK(0);
; #pragma unroll
;     for (int ks = 0; ks < 4; ++ks) {
;         if (ks + 1 < 4) ATT_VREADK(ks + 1);
;         osum = __builtin_amdgcn_mfma_f32_32x32x16_bf16(pp[ks], ones, osum, 0, 0, 0);
; #pragma unroll
;         for (int d = 0; d < 4; ++d) { const int bk = ks & 1;
;             const bf16x8 vf = (bf16x8){vl[bk][d][0], vl[bk][d][1], vl[bk][d][2], vl[bk][d][3], vh[bk][d][0], vh[bk][d][1], vh[bk][d][2], vh[bk][d][3]};
;             o[d] = __builtin_amdgcn_mfma_f32_32x32x16_bf16(pp[ks], vf, o[d], 0, 0, 0); }
;     }
.Latt_fast_exit:
	s_waitcnt vmcnt(4) lgkmcnt(0)
	s_barrier
	v_exp_f32_e32 v2, v2
	v_exp_f32_e32 v3, v3
	v_add_f32_e32 v243, v243, v2
	v_exp_f32_e32 v4, v4
	v_add_f32_e32 v244, v244, v3
	v_exp_f32_e32 v5, v5
	v_add_f32_e32 v243, v243, v4
	v_cvt_pk_bf16_f32 v124, v2, v3
	v_add_f32_e32 v244, v244, v5
	v_exp_f32_e32 v6, v6
	v_exp_f32_e32 v7, v7
	v_add_f32_e32 v243, v243, v6
	v_cvt_pk_bf16_f32 v125, v4, v5
	v_add_f32_e32 v244, v244, v7
	v_exp_f32_e32 v8, v8
	v_exp_f32_e32 v9, v9
	v_add_f32_e32 v243, v243, v8
	v_cvt_pk_bf16_f32 v126, v6, v7
	v_add_f32_e32 v244, v244, v9
	v_cvt_pk_bf16_f32 v127, v8, v9
	v_exp_f32_e32 v10, v10
	v_exp_f32_e32 v11, v11
	v_add_f32_e32 v243, v243, v10
	v_exp_f32_e32 v12, v12
	v_add_f32_e32 v244, v244, v11
	v_exp_f32_e32 v13, v13
	v_add_f32_e32 v243, v243, v12
	v_cvt_pk_bf16_f32 v120, v10, v11
	v_add_f32_e32 v244, v244, v13
	v_exp_f32_e32 v14, v14
	v_exp_f32_e32 v15, v15
	v_add_f32_e32 v243, v243, v14
	v_cvt_pk_bf16_f32 v121, v12, v13
	v_add_f32_e32 v244, v244, v15
	v_exp_f32_e32 v16, v16
	v_exp_f32_e32 v17, v17
	v_add_f32_e32 v243, v243, v16
	v_cvt_pk_bf16_f32 v122, v14, v15
	v_add_f32_e32 v244, v244, v17
	v_cvt_pk_bf16_f32 v123, v16, v17
	s_add_i32 s10, s57, 0xffff4000
	s_and_b32 s10, s10, 0xc000
	v_add_u32_e32 v133, s10, v185
	ds_read_b64_tr_b16 v[128:129], v133
	ds_read_b64_tr_b16 v[130:131], v133 offset:512
	ds_read_b64_tr_b16 v[138:139], v133 offset:4096
	ds_read_b64_tr_b16 v[140:141], v133 offset:4608
	ds_read_b64_tr_b16 v[142:143], v133 offset:8192
	ds_read_b64_tr_b16 v[144:145], v133 offset:8704
	ds_read_b64_tr_b16 v[250:251], v133 offset:12288
	ds_read_b64_tr_b16 v[252:253], v133 offset:12800
	s_waitcnt lgkmcnt(6)
	v_mfma_f32_32x32x16_bf16 v[34:49], v[134:137], v[128:131], v[34:49]
	ds_read_b64_tr_b16 v[128:129], v133 offset:1024
	ds_read_b64_tr_b16 v[130:131], v133 offset:1536
	s_waitcnt lgkmcnt(6)
	v_mfma_f32_32x32x16_bf16 v[50:65], v[134:137], v[138:141], v[50:65]
	ds_read_b64_tr_b16 v[138:139], v133 offset:5120
	ds_read_b64_tr_b16 v[140:141], v133 offset:5632
	s_waitcnt lgkmcnt(6)
	v_mfma_f32_32x32x16_bf16 v[66:81], v[134:137], v[142:145], v[66:81]
	ds_read_b64_tr_b16 v[142:143], v133 offset:9216
	ds_read_b64_tr_b16 v[144:145], v133 offset:9728
	s_waitcnt lgkmcnt(6)
	v_mfma_f32_32x32x16_bf16 v[82:97], v[134:137], v[250:253], v[82:97]
	ds_read_b64_tr_b16 v[250:251], v133 offset:13312
	ds_read_b64_tr_b16 v[252:253], v133 offset:13824
	s_waitcnt lgkmcnt(6)
	v_mfma_f32_32x32x16_bf16 v[34:49], v[114:117], v[128:131], v[34:49]
	ds_read_b64_tr_b16 v[128:129], v133 offset:2048
	ds_read_b64_tr_b16 v[130:131], v133 offset:2560
	s_waitcnt lgkmcnt(6)
	v_mfma_f32_32x32x16_bf16 v[50:65], v[114:117], v[138:141], v[50:65]
	ds_read_b64_tr_b16 v[138:139], v133 offset:6144
	ds_read_b64_tr_b16 v[140:141], v133 offset:6656
	s_waitcnt lgkmcnt(6)
	v_mfma_f32_32x32x16_bf16 v[66:81], v[114:117], v[142:145], v[66:81]
	ds_read_b64_tr_b16 v[142:143], v133 offset:10240
	ds_read_b64_tr_b16 v[144:145], v133 offset:10752
	s_waitcnt lgkmcnt(6)
	v_mfma_f32_32x32x16_bf16 v[82:97], v[114:117], v[250:253], v[82:97]
	ds_read_b64_tr_b16 v[250:251], v133 offset:14336
	ds_read_b64_tr_b16 v[252:253], v133 offset:14848
	s_waitcnt lgkmcnt(6)
	v_mfma_f32_32x32x16_bf16 v[34:49], v[124:127], v[128:131], v[34:49]
	ds_read_b64_tr_b16 v[128:129], v133 offset:3072
	ds_read_b64_tr_b16 v[130:131], v133 offset:3584
	s_waitcnt lgkmcnt(6)
	v_mfma_f32_32x32x16_bf16 v[50:65], v[124:127], v[138:141], v[50:65]
	ds_read_b64_tr_b16 v[138:139], v133 offset:7168
	ds_read_b64_tr_b16 v[140:141], v133 offset:7680
	s_waitcnt lgkmcnt(6)
	v_mfma_f32_32x32x16_bf16 v[66:81], v[124:127], v[142:145], v[66:81]
	ds_read_b64_tr_b16 v[142:143], v133 offset:11264
	ds_read_b64_tr_b16 v[144:145], v133 offset:11776
	s_waitcnt lgkmcnt(6)
	v_mfma_f32_32x32x16_bf16 v[82:97], v[124:127], v[250:253], v[82:97]
	ds_read_b64_tr_b16 v[250:251], v133 offset:15360
	ds_read_b64_tr_b16 v[252:253], v133 offset:15872
	s_waitcnt lgkmcnt(6)
	v_mfma_f32_32x32x16_bf16 v[34:49], v[120:123], v[128:131], v[34:49]
	s_waitcnt lgkmcnt(4)
	v_mfma_f32_32x32x16_bf16 v[50:65], v[120:123], v[138:141], v[50:65]
	s_waitcnt lgkmcnt(2)
	v_mfma_f32_32x32x16_bf16 v[66:81], v[120:123], v[142:145], v[66:81]
	s_waitcnt lgkmcnt(0)
	v_mfma_f32_32x32x16_bf16 v[82:97], v[120:123], v[250:253], v[82:97]
	v_add_f32_e32 v243, v243, v244
	v_mov_b32_e32 v244, v243
	s_nop 1
	v_permlane32_swap_b32_e32 v243, v244
	v_add_f32_e32 v243, v243, v244
	s_and_saveexec_b64 s[10:11], s[6:7]
	ds_write_b32 v224, v243
	s_or_b64 exec, exec, s[10:11]
	s_waitcnt lgkmcnt(0)
	v_add_u32_e32 v132, s51, v187
	ds_read_b128 v[128:131], v132
	ds_read_b128 v[138:141], v132 offset:32
	ds_read_b128 v[142:145], v132 offset:64
	ds_read_b128 v[250:253], v132 offset:96
	v_mov_b32_e32 v17, v248
	v_mov_b32_e32 v16, v118
	s_waitcnt lgkmcnt(0)
	v_add_f32_e32 v18, v18, v128
	v_add_f32_e32 v19, v19, v129
	v_add_f32_e32 v20, v20, v130
	v_add_f32_e32 v21, v21, v131
	v_add_f32_e32 v22, v22, v138
	v_add_f32_e32 v23, v23, v139
	v_add_f32_e32 v24, v24, v140
	v_add_f32_e32 v25, v25, v141
	v_add_f32_e32 v26, v26, v142
	v_add_f32_e32 v27, v27, v143
	v_add_f32_e32 v28, v28, v144
	v_add_f32_e32 v29, v29, v145
	v_add_f32_e32 v30, v30, v250
	v_add_f32_e32 v31, v31, v251
	v_add_f32_e32 v32, v32, v252
	v_add_f32_e32 v33, v33, v253
	s_cmp_eq_u32 s50, s56
	s_cbranch_scc1 .LBB0_695
	s_branch .LBB0_686
; __device__ __forceinline__ unsigned pk2(float lo, float hi) { f32x2_t v = {lo, hi}; bf16x2_t b = __builtin_convertvector(v, bf16x2_t); return __builtin_bit_cast(unsigned, b); }
; __device__ __forceinline__ int crow(int r, int hi) { return (r & 3) + 8 * (r >> 2) + 4 * hi; }
; __device__ __forceinline__ void att_qs(bf16x8 (&pn)[4], f32x16 (&o)[4], f32x16& osum, f32x16& negm, const bf16x8 (&qf)[4], float& m_hat, ...
;     ...
;     } else if (__any(rm > 8.0f)) {
;         const float dl = fmaxf(rm, 0.f); m_hat += dl; const float f = __builtin_amdgcn_exp2f(-dl);
; #pragma unroll
;         for (int r = 0; r < 16; ++r) { c0[r] -= dl; c1[r] -= dl; negm[r] = -m_hat; }
;         if (hi == 0) scr[i32] = f;
;         asm volatile("s_waitcnt lgkmcnt(0)" ::: "memory");
; #pragma unroll
;         for (int r = 0; r < 16; ++r) { const float fr_ = scr[crow(r, hi)]; osum[r] *= fr_;
; #pragma unroll
;             for (int d = 0; d < 4; ++d) o[d][r] *= fr_; }
;     }
;     unsigned paw[16];
; #pragma unroll
;     for (int g = 0; g < 8; ++g) { const int b = (4 * g) & 15;
;         const float v0 = __builtin_amdgcn_exp2f(g < 4 ? c0[b] : c1[b]), v1 = __builtin_amdgcn_exp2f(g < 4 ? c0[b + 1] : c1[b + 1]);
;         const float v2 = __builtin_amdgcn_exp2f(g < 4 ? c0[b + 2] : c1[b + 2]), v3 = __builtin_amdgcn_exp2f(g < 4 ? c0[b + 3] : c1[b + 3]);
;         paw[2 * g] = pk2(v0, v1); paw[2 * g + 1] = pk2(v2, v3); }
; #pragma unroll
;     for (int k = 0; k < 4; ++k) { u32x4 w; w.x = paw[4 * k]; w.y = paw[4 * k + 1]; w.z = paw[4 * k + 2]; w.w = paw[4 * k + 3]; pn[k] = __builtin_bit_cast(bf16x8, w); }
.Latt_fast_rescale:
	s_waitcnt lgkmcnt(0)
	v_mfma_f32_32x32x16_bf16 v[34:49], v[124:127], v[128:131], v[34:49]
	v_mfma_f32_32x32x16_bf16 v[50:65], v[124:127], v[138:141], v[50:65]
	v_mfma_f32_32x32x16_bf16 v[66:81], v[124:127], v[142:145], v[66:81]
	v_mfma_f32_32x32x16_bf16 v[82:97], v[124:127], v[250:253], v[82:97]
	ds_read_b64_tr_b16 v[128:129], v133 offset:3072
	ds_read_b64_tr_b16 v[130:131], v133 offset:3584
	ds_read_b64_tr_b16 v[138:139], v133 offset:7168
	ds_read_b64_tr_b16 v[140:141], v133 offset:7680
	ds_read_b64_tr_b16 v[142:143], v133 offset:11264
	ds_read_b64_tr_b16 v[144:145], v133 offset:11776
	ds_read_b64_tr_b16 v[250:251], v133 offset:15360
	ds_read_b64_tr_b16 v[252:253], v133 offset:15872
	s_waitcnt lgkmcnt(0)
	v_mfma_f32_32x32x16_bf16 v[34:49], v[120:123], v[128:131], v[34:49]
	v_mfma_f32_32x32x16_bf16 v[50:65], v[120:123], v[138:141], v[50:65]
	v_mfma_f32_32x32x16_bf16 v[66:81], v[120:123], v[142:145], v[66:81]
	v_mfma_f32_32x32x16_bf16 v[82:97], v[120:123], v[250:253], v[82:97]
	s_nop 15
	v_max_f32_e32 v0, 0, v0
	v_add_f32_e32 v248, v248, v0
	v_exp_f32_e64 v225, -v0
	s_and_saveexec_b64 s[10:11], s[6:7]
	ds_write_b32 v224, v225
	s_or_b64 exec, exec, s[10:11]
	v_mul_f32_e32 v243, v243, v225
	v_mul_f32_e32 v244, v244, v225
	s_waitcnt lgkmcnt(0)
	v_add_u32_e32 v132, s51, v187
	ds_read_b128 v[128:131], v132
	ds_read_b128 v[138:141], v132 offset:32
	ds_read_b128 v[142:145], v132 offset:64
	ds_read_b128 v[250:253], v132 offset:96
	v_sub_f32_e32 v226, v226, v0
	v_sub_f32_e32 v227, v227, v0
	v_sub_f32_e32 v228, v228, v0
	v_sub_f32_e32 v229, v229, v0
	v_sub_f32_e32 v230, v230, v0
	v_sub_f32_e32 v231, v231, v0
	v_sub_f32_e32 v232, v232, v0
	v_sub_f32_e32 v233, v233, v0
	v_sub_f32_e32 v234, v234, v0
	v_sub_f32_e32 v235, v235, v0
	v_sub_f32_e32 v236, v236, v0
	v_sub_f32_e32 v237, v237, v0
	v_sub_f32_e32 v238, v238, v0
	v_sub_f32_e32 v239, v239, v0
	v_sub_f32_e32 v240, v240, v0
	v_sub_f32_e32 v241, v241, v0
	v_sub_f32_e32 v2, v2, v0
	v_sub_f32_e32 v3, v3, v0
	v_sub_f32_e32 v4, v4, v0
	v_sub_f32_e32 v5, v5, v0
	v_sub_f32_e32 v6, v6, v0
	v_sub_f32_e32 v7, v7, v0
	v_sub_f32_e32 v8, v8, v0
	v_sub_f32_e32 v9, v9, v0
	v_sub_f32_e32 v10, v10, v0
	v_sub_f32_e32 v11, v11, v0
	v_sub_f32_e32 v12, v12, v0
	v_sub_f32_e32 v13, v13, v0
	v_sub_f32_e32 v14, v14, v0
	v_sub_f32_e32 v15, v15, v0
	v_sub_f32_e32 v16, v16, v0
	v_sub_f32_e32 v17, v17, v0
	v_xor_b32_e32 v98, 0x80000000, v248
	v_mov_b32_e32 v99, v98
	v_mov_b32_e32 v100, v98
	v_mov_b32_e32 v101, v98
	v_mov_b32_e32 v102, v98
	v_mov_b32_e32 v103, v98
	v_mov_b32_e32 v104, v98
	v_mov_b32_e32 v105, v98
	v_mov_b32_e32 v106, v98
	v_mov_b32_e32 v107, v98
	v_mov_b32_e32 v108, v98
	v_mov_b32_e32 v109, v98
	v_mov_b32_e32 v110, v98
	v_mov_b32_e32 v111, v98
	v_mov_b32_e32 v112, v98
	v_mov_b32_e32 v113, v98
	s_waitcnt lgkmcnt(0)
	v_mul_f32_e32 v18, v18, v128
	v_mul_f32_e32 v34, v34, v128
	v_mul_f32_e32 v50, v50, v128
	v_mul_f32_e32 v66, v66, v128
	v_mul_f32_e32 v82, v82, v128
	v_mul_f32_e32 v19, v19, v129
	v_mul_f32_e32 v35, v35, v129
	v_mul_f32_e32 v51, v51, v129
	v_mul_f32_e32 v67, v67, v129
	v_mul_f32_e32 v83, v83, v129
	v_mul_f32_e32 v20, v20, v130
	v_mul_f32_e32 v36, v36, v130
	v_mul_f32_e32 v52, v52, v130
	v_mul_f32_e32 v68, v68, v130
	v_mul_f32_e32 v84, v84, v130
	v_mul_f32_e32 v21, v21, v131
	v_mul_f32_e32 v37, v37, v131
	v_mul_f32_e32 v53, v53, v131
	v_mul_f32_e32 v69, v69, v131
	v_mul_f32_e32 v85, v85, v131
	v_mul_f32_e32 v22, v22, v138
	v_mul_f32_e32 v38, v38, v138
	v_mul_f32_e32 v54, v54, v138
	v_mul_f32_e32 v70, v70, v138
	v_mul_f32_e32 v86, v86, v138
	v_mul_f32_e32 v23, v23, v139
	v_mul_f32_e32 v39, v39, v139
	v_mul_f32_e32 v55, v55, v139
	v_mul_f32_e32 v71, v71, v139
	v_mul_f32_e32 v87, v87, v139
	v_mul_f32_e32 v24, v24, v140
	v_mul_f32_e32 v40, v40, v140
	v_mul_f32_e32 v56, v56, v140
	v_mul_f32_e32 v72, v72, v140
	v_mul_f32_e32 v88, v88, v140
	v_mul_f32_e32 v25, v25, v141
	v_mul_f32_e32 v41, v41, v141
	v_mul_f32_e32 v57, v57, v141
	v_mul_f32_e32 v73, v73, v141
	v_mul_f32_e32 v89, v89, v141
	v_mul_f32_e32 v26, v26, v142
	v_mul_f32_e32 v42, v42, v142
	v_mul_f32_e32 v58, v58, v142
	v_mul_f32_e32 v74, v74, v142
	v_mul_f32_e32 v90, v90, v142
	v_mul_f32_e32 v27, v27, v143
	v_mul_f32_e32 v43, v43, v143
	v_mul_f32_e32 v59, v59, v143
	v_mul_f32_e32 v75, v75, v143
	v_mul_f32_e32 v91, v91, v143
	v_mul_f32_e32 v28, v28, v144
	v_mul_f32_e32 v44, v44, v144
	v_mul_f32_e32 v60, v60, v144
	v_mul_f32_e32 v76, v76, v144
	v_mul_f32_e32 v92, v92, v144
	v_mul_f32_e32 v29, v29, v145
	v_mul_f32_e32 v45, v45, v145
	v_mul_f32_e32 v61, v61, v145
	v_mul_f32_e32 v77, v77, v145
	v_mul_f32_e32 v93, v93, v145
	v_mul_f32_e32 v30, v30, v250
	v_mul_f32_e32 v46, v46, v250
	v_mul_f32_e32 v62, v62, v250
	v_mul_f32_e32 v78, v78, v250
	v_mul_f32_e32 v94, v94, v250
	v_mul_f32_e32 v31, v31, v251
	v_mul_f32_e32 v47, v47, v251
	v_mul_f32_e32 v63, v63, v251
	v_mul_f32_e32 v79, v79, v251
	v_mul_f32_e32 v95, v95, v251
	v_mul_f32_e32 v32, v32, v252
	v_mul_f32_e32 v48, v48, v252
	v_mul_f32_e32 v64, v64, v252
	v_mul_f32_e32 v80, v80, v252
	v_mul_f32_e32 v96, v96, v252
	v_mul_f32_e32 v33, v33, v253
	v_mul_f32_e32 v49, v49, v253
	v_mul_f32_e32 v65, v65, v253
	v_mul_f32_e32 v81, v81, v253
	v_mul_f32_e32 v97, v97, v253
	v_exp_f32_e32 v226, v226
	v_exp_f32_e32 v227, v227
	v_add_f32_e32 v243, v243, v226
	v_exp_f32_e32 v228, v228
	v_add_f32_e32 v244, v244, v227
	v_exp_f32_e32 v229, v229
	v_add_f32_e32 v243, v243, v228
	v_cvt_pk_bf16_f32 v134, v226, v227
	v_add_f32_e32 v244, v244, v229
	v_exp_f32_e32 v230, v230
	v_exp_f32_e32 v231, v231
	v_add_f32_e32 v243, v243, v230
	v_cvt_pk_bf16_f32 v135, v228, v229
	v_add_f32_e32 v244, v244, v231
	v_exp_f32_e32 v232, v232
	v_exp_f32_e32 v233, v233
	v_add_f32_e32 v243, v243, v232
	v_cvt_pk_bf16_f32 v136, v230, v231
	v_add_f32_e32 v244, v244, v233
	v_cvt_pk_bf16_f32 v137, v232, v233
	v_exp_f32_e32 v234, v234
	v_exp_f32_e32 v235, v235
	v_add_f32_e32 v243, v243, v234
	v_exp_f32_e32 v236, v236
	v_add_f32_e32 v244, v244, v235
	v_exp_f32_e32 v237, v237
	v_add_f32_e32 v243, v243, v236
	v_cvt_pk_bf16_f32 v114, v234, v235
	v_add_f32_e32 v244, v244, v237
	v_exp_f32_e32 v238, v238
	v_exp_f32_e32 v239, v239
	v_add_f32_e32 v243, v243, v238
	v_cvt_pk_bf16_f32 v115, v236, v237
	v_add_f32_e32 v244, v244, v239
	v_exp_f32_e32 v240, v240
	v_exp_f32_e32 v241, v241
	v_add_f32_e32 v243, v243, v240
	v_cvt_pk_bf16_f32 v116, v238, v239
	v_add_f32_e32 v244, v244, v241
	v_cvt_pk_bf16_f32 v117, v240, v241
	s_waitcnt lgkmcnt(0)
	s_add_i32 s58, s57, 0xffffc000
	s_and_b32 s58, s58, 0xc000
	v_add_u32_e32 v132, s58, v177
	ds_read_b128 v[128:131], v132
	ds_read_b128 v[138:141], v132 offset:2048
	ds_read_b128 v[142:145], v132 offset:4096
	ds_read_b128 v[250:253], v132 offset:6144
	s_branch .Latt_fast_end

; #define ATT_COMMON(tt) \
;         const int kp0_ = TILE_POS(tt); const bool near_ = (kp0_ + 63 - qp_w) >= -90; const int lb_ = kp0_ - qpos + 128; const LAS unsigned char* kb_ = kfb + ((tt) & 3) * 16384;
; __device__ __forceinline__ void attn_unit(LAS unsigned char* lds, const bf16_t* Qb, const unsigned char* Kimg, const unsigned char* Vimg, bf16_t* AO, int b, int h, int qpos0, int ntiles, int store_limit, ...
;     ...
;         for (int tt = 0; tt < ntiles; ++tt) {
;             ATT_COMMON(tt)
;             if (tt >= 1 && tt - 1 <= T_w) att_pv(pn, o, osum, vfb + ((tt - 1) & 3) * 16384);
;             if (tt <= T_w) att_qs(pn, o, osum, negm, qf, m_hat, kb_, scr, lut, hi, i32, near_, lb_, tt == 0);
.LBB0_684:
	s_cmp_le_u32 s56, s54
	s_cbranch_scc0 .Latt_old_iter
	s_cmpk_lt_i32 s55, 0xffa6
	s_cbranch_scc1 .Latt_fast_entry

; #define ATT_WAITBAR(N) asm volatile("s_waitcnt vmcnt(" #N ") lgkmcnt(0)\n\ts_barrier" ::: "memory")
; #define ATT_COMMON(tt) \
;         const int kp0_ = TILE_POS(tt); const bool near_ = (kp0_ + 63 - qp_w) >= -90; const int lb_ = kp0_ - qpos + 128; const LAS unsigned char* kb_ = kfb + ((tt) & 3) * 16384;
; __device__ __forceinline__ void attn_unit(LAS unsigned char* lds, const bf16_t* Qb, const unsigned char* Kimg, const unsigned char* Vimg, bf16_t* AO, int b, int h, int qpos0, int ntiles, int store_limit, ...
;     ...
;     if (c == 0) {
;         for (int tt = 0; tt < ntiles; ++tt) {
;             ATT_COMMON(tt)
;             if (tt <= T_w) att_qs(pn, o, osum, negm, qf, m_hat, kb_, scr, lut, hi, i32, near_, lb_, tt == 0);
;             DMA_TILE(tt + 2);
;             if (tt <= T_w) att_pv(pn, o, osum, vfb + (tt & 3) * 16384);
;             ATT_WAITBAR(4);
;         }
;     } else {
;     ...
;     { const float num = (c == 0 ? 1.0f : -lam);
.LBB0_695:
.LBB0_696:
	v_cmp_gt_u32_e32 vcc, 0x100, v163
	v_mov_b32_e32 v4, 1.0
	s_nop 1
	v_cndmask_b32_e32 v4, v188, v4, vcc

; __global__ void __launch_bounds__(512, 2) fwd_kernel(Args a) {
;     extern __shared__ __attribute__((aligned(16))) unsigned char shm_raw[];
	.amdhsa_kernel _Z10fwd_kernel4Args
		.amdhsa_group_segment_fixed_size 0
		.amdhsa_private_segment_fixed_size 0
		.amdhsa_kernarg_size 496
		.amdhsa_user_sgpr_count 2
		.amdhsa_user_sgpr_dispatch_ptr 0
		.amdhsa_user_sgpr_queue_ptr 0
		.amdhsa_user_sgpr_kernarg_segment_ptr 1
		.amdhsa_user_sgpr_dispatch_id 0
		.amdhsa_user_sgpr_kernarg_preload_length 0
		.amdhsa_user_sgpr_kernarg_preload_offset 0
		.amdhsa_user_sgpr_private_segment_size 0
		.amdhsa_uses_dynamic_stack 0
		.amdhsa_enable_private_segment 0
		.amdhsa_system_sgpr_workgroup_id_x 1
		.amdhsa_system_sgpr_workgroup_id_y 0
		.amdhsa_system_sgpr_workgroup_id_z 0
		.amdhsa_system_sgpr_workgroup_info 0
		.amdhsa_system_vgpr_workitem_id 2
		.amdhsa_next_free_vgpr 256
		.amdhsa_next_free_sgpr 102
		.amdhsa_accum_offset 256
		.amdhsa_reserve_vcc 1
		.amdhsa_float_round_mode_32 0
		.amdhsa_float_round_mode_16_64 0
		.amdhsa_float_denorm_mode_32 3
		.amdhsa_float_denorm_mode_16_64 3
		.amdhsa_dx10_clamp 1
		.amdhsa_ieee_mode 1
		.amdhsa_fp16_overflow 0
		.amdhsa_tg_split 0
		.amdhsa_exception_fp_ieee_invalid_op 0
		.amdhsa_exception_fp_denorm_src 0
		.amdhsa_exception_fp_ieee_div_zero 0
		.amdhsa_exception_fp_ieee_overflow 0
		.amdhsa_exception_fp_ieee_underflow 0
		.amdhsa_exception_fp_ieee_inexact 0
		.amdhsa_exception_int_div_zero 0
	.end_amdhsa_kernel

; __global__ void __launch_bounds__(512, 2) fwd_kernel(Args a) {
;     extern __shared__ __attribute__((aligned(16))) unsigned char shm_raw[];
amdhsa.kernels:
  - .agpr_count:     0
    .args:
      - .offset:         0
        .size:           240
        .value_kind:     by_value
      - .offset:         240
        .size:           4
        .value_kind:     hidden_block_count_x
      - .offset:         244
        .size:           4
        .value_kind:     hidden_block_count_y
      - .offset:         248
        .size:           4
        .value_kind:     hidden_block_count_z
      - .offset:         252
        .size:           2
        .value_kind:     hidden_group_size_x
      - .offset:         254
        .size:           2
        .value_kind:     hidden_group_size_y
      - .offset:         256
        .size:           2
        .value_kind:     hidden_group_size_z
      - .offset:         258
        .size:           2
        .value_kind:     hidden_remainder_x
      - .offset:         260
        .size:           2
        .value_kind:     hidden_remainder_y
      - .offset:         262
        .size:           2
        .value_kind:     hidden_remainder_z
      - .offset:         280
        .size:           8
        .value_kind:     hidden_global_offset_x
      - .offset:         288
        .size:           8
        .value_kind:     hidden_global_offset_y
      - .offset:         296
        .size:           8
        .value_kind:     hidden_global_offset_z
      - .offset:         304
        .size:           2
        .value_kind:     hidden_grid_dims
      - .offset:         328
        .size:           8
        .value_kind:     hidden_multigrid_sync_arg
      - .offset:         360
        .size:           4
        .value_kind:     hidden_dynamic_lds_size
    .group_segment_fixed_size: 0
    .kernarg_segment_align: 8
    .kernarg_segment_size: 496
    .language:       OpenCL C
    .language_version:
      - 2
      - 0
    .max_flat_workgroup_size: 512
    .name:           _Z10fwd_kernel4Args
    .private_segment_fixed_size: 0
    .sgpr_count:     108
    .sgpr_spill_count: 68
    .symbol:         _Z10fwd_kernel4Args.kd
    .uniform_work_group_size: 1
    .uses_dynamic_stack: false
    .vgpr_count:     256
    .vgpr_spill_count: 0
    .wavefront_size: 64
